# norm phase writes H with write-through (sc1) stores so the release write-back at the next barrier is short
# speedup vs baseline: 1.0439x; 1.0043x over previous
; #define NORM_LOAD(V, ROW) do { const u32x2* xr_ = (const u32x2*)(X + (size_t)(ROW) * D); _Pragma("unroll") for (int j = 0; j < 4; ++j) { const u32x2 w_ = xr_[64 * j + lane]; \
;         V[j] = (f32x4){__uint_as_float(w_.x << 16), __uint_as_float(w_.x & 0xffff0000u), __uint_as_float(w_.y << 16), __uint_as_float(w_.y & 0xffff0000u)}; } } while (0)
; __device__ __forceinline__ void p_norm(const Args& a, int l, int lane, int wave, int bid, int G) {
;     ...
;         for (int r0 = gw; r0 < LP; r0 += 3 * NGW) {
;             f32x4 v0[4], v1[4], v2[4];
;             const int ra = n * LP + r0, rb = ra + NGW, rc = rb + NGW;
;             const bool hb = r0 + NGW < LP, hc = r0 + 2 * NGW < LP;
;             NORM_LOAD(v0, ra); if (hb) NORM_LOAD(v1, rb); if (hc) NORM_LOAD(v2, rc);
;             NORM_FINISH(v0, ra, gs, sh); if (hb) NORM_FINISH(v1, rb, gs, sh); if (hc) NORM_FINISH(v2, rc, gs, sh);
.LBB0_200:
	s_waitcnt vmcnt(3)
	v_lshlrev_b32_e32 v86, 16, v78
	v_and_b32_e32 v87, 0xffff0000, v78
	v_lshlrev_b32_e32 v78, 16, v79
	v_and_b32_e32 v79, 0xffff0000, v79
	s_waitcnt vmcnt(0)
	v_lshlrev_b32_e32 v93, 16, v72
	v_mul_f32_e32 v92, v79, v79
	v_lshlrev_b32_e32 v89, 16, v77
	v_lshlrev_b32_e32 v88, 16, v76
	v_and_b32_e32 v77, 0xffff0000, v77
	v_and_b32_e32 v76, 0xffff0000, v76
	v_pk_fma_f32 v[96:97], v[78:79], v[78:79], v[92:93] op_sel_hi:[1,1,0]
	v_mul_f32_e32 v92, v87, v87
	v_pk_mul_f32 v[98:99], v[76:77], v[76:77]
	v_pk_fma_f32 v[100:101], v[86:87], v[86:87], v[92:93] op_sel_hi:[1,1,0]
	v_and_b32_e32 v95, 0xffff0000, v72
	v_pk_fma_f32 v[98:99], v[88:89], v[88:89], v[98:99]
	v_mov_b32_e32 v92, v100
	v_mov_b32_e32 v102, v96
	v_mov_b32_e32 v103, v93
	v_and_b32_e32 v91, 0xffff0000, v74
	v_mul_f32_e32 v85, v95, v95
	v_pk_add_f32 v[96:97], v[100:101], v[96:97]
	v_pk_mul_f32 v[100:101], v[92:93], v[102:103]
	v_pk_add_f32 v[98:99], v[98:99], v[98:99] op_sel:[0,1] op_sel_hi:[1,0]
	v_lshlrev_b32_e32 v90, 16, v74
	v_lshlrev_b32_e32 v74, 16, v75
	v_and_b32_e32 v75, 0xffff0000, v75
	v_mov_b32_e32 v97, v101
	v_mov_b32_e32 v99, v85
	v_mul_f32_e32 v92, v91, v91
	v_lshlrev_b32_e32 v72, 16, v73
	v_and_b32_e32 v73, 0xffff0000, v73
	v_pk_add_f32 v[96:97], v[96:97], v[98:99]
	v_pk_fma_f32 v[98:99], v[90:91], v[90:91], v[92:93] op_sel_hi:[1,1,0]
	v_mul_f32_e32 v92, v75, v75
	v_mul_f32_e32 v94, v72, v72
	v_mul_f32_e32 v104, v73, v73
	v_pk_fma_f32 v[100:101], v[74:75], v[74:75], v[92:93] op_sel_hi:[1,1,0]
	v_mov_b32_e32 v99, v94
	v_mov_b32_e32 v101, v104
	v_pk_add_f32 v[98:99], v[98:99], v[100:101]
	v_mov_b32_e32 v94, v93
	v_pk_add_f32 v[96:97], v[96:97], v[98:99]
	s_lshl_b64 s[16:17], s[16:17], 10
	v_add_f32_e32 v85, v96, v97
	ds_bpermute_b32 v92, v51, v85
	v_lshl_add_u64 v[96:97], s[16:17], 1, v[52:53]
	s_waitcnt lgkmcnt(0)
	v_add_f32_e32 v85, v85, v92
	ds_bpermute_b32 v92, v80, v85
	s_waitcnt lgkmcnt(0)
	v_add_f32_e32 v85, v85, v92
	ds_bpermute_b32 v92, v81, v85
	s_waitcnt lgkmcnt(0)
	v_add_f32_e32 v85, v85, v92
	ds_bpermute_b32 v92, v82, v85
	s_waitcnt lgkmcnt(0)
	v_add_f32_e32 v85, v85, v92
	ds_bpermute_b32 v92, v83, v85
	s_waitcnt lgkmcnt(0)
	v_add_f32_e32 v85, v85, v92
	ds_bpermute_b32 v92, v84, v85
	s_waitcnt lgkmcnt(0)
	v_add_f32_e32 v85, v85, v92
	v_fmamk_f32 v85, v85, 0x3a800000, v209
	v_mul_f32_e32 v92, 0x4b800000, v85
	v_cmp_gt_f32_e32 vcc, s96, v85
	s_nop 1
	v_cndmask_b32_e32 v85, v85, v92, vcc
	v_rsq_f32_e32 v85, v85
	s_nop 0
	v_mul_f32_e32 v92, 0x45800000, v85
	v_cndmask_b32_e32 v92, v85, v92, vcc
	v_pk_mul_f32 v[86:87], v[92:93], v[86:87] op_sel_hi:[0,1]
	v_pk_mul_f32 v[78:79], v[92:93], v[78:79] op_sel_hi:[0,1]
	v_pk_fma_f32 v[78:79], v[68:69], v[78:79], v[34:35]
	v_pk_fma_f32 v[86:87], v[70:71], v[86:87], v[32:33]
	v_pk_mul_f32 v[74:75], v[92:93], v[74:75] op_sel_hi:[0,1]
	v_cvt_pk_bf16_f32 v86, v86, v87
	v_cvt_pk_bf16_f32 v87, v78, v79
	v_mov_b32_e32 v78, v88
	v_mov_b32_e32 v79, v76
	v_mov_b32_e32 v76, v89
	v_pk_mul_f32 v[78:79], v[92:93], v[78:79] op_sel_hi:[0,1]
	v_pk_mul_f32 v[76:77], v[92:93], v[76:77] op_sel_hi:[0,1]
	v_pk_fma_f32 v[76:77], v[56:57], v[76:77], v[38:39]
	v_pk_fma_f32 v[78:79], v[58:59], v[78:79], v[36:37]
	v_pk_fma_f32 v[74:75], v[60:61], v[74:75], v[42:43]
	v_cvt_pk_bf16_f32 v78, v78, v79
	v_cvt_pk_bf16_f32 v79, v76, v77
	v_pk_mul_f32 v[76:77], v[92:93], v[90:91] op_sel_hi:[0,1]
	v_pk_fma_f32 v[76:77], v[62:63], v[76:77], v[40:41]
	v_pk_mul_f32 v[72:73], v[92:93], v[72:73] op_sel_hi:[0,1]
	v_cvt_pk_bf16_f32 v76, v76, v77
	v_cvt_pk_bf16_f32 v77, v74, v75
	v_pk_mul_f32 v[74:75], v[92:93], v[94:95] op_sel_hi:[0,1]
	v_pk_fma_f32 v[72:73], v[64:65], v[72:73], v[46:47]
	v_pk_fma_f32 v[74:75], v[66:67], v[74:75], v[44:45]
	s_andn2_b64 vcc, exec, s[14:15]
	v_cvt_pk_bf16_f32 v74, v74, v75
	v_cvt_pk_bf16_f32 v75, v72, v73
	global_store_dwordx2 v[96:97], v[86:87], off sc1
	global_store_dwordx2 v[96:97], v[78:79], off offset:512 sc1
	global_store_dwordx2 v[96:97], v[76:77], off offset:1024 sc1
	global_store_dwordx2 v[96:97], v[74:75], off offset:1536 sc1
	s_cbranch_vccnz .LBB0_202
; __device__ __forceinline__ void p_norm(const Args& a, int l, int lane, int wave, int bid, int G) {
;     ...
;             NORM_FINISH(v0, ra, gs, sh); if (hb) NORM_FINISH(v1, rb, gs, sh); if (hc) NORM_FINISH(v2, rc, gs, sh);
	v_pk_mul_f32 v[72:73], v[6:7], v[6:7]
	v_pk_mul_f32 v[74:75], v[4:5], v[4:5]
	s_ashr_i32 s11, s10, 31
	v_pk_mov_b32 v[76:77], v[74:75], v[72:73] op_sel:[1,0]
	v_mov_b32_e32 v75, v73
	v_pk_add_f32 v[72:73], v[76:77], v[74:75]
	v_pk_mul_f32 v[74:75], v[14:15], v[14:15]
	v_pk_mul_f32 v[76:77], v[12:13], v[12:13]
	v_pk_add_f32 v[72:73], v[72:73], v[72:73] op_sel:[0,1] op_sel_hi:[1,0]
	v_pk_mov_b32 v[78:79], v[76:77], v[74:75] op_sel:[1,0]
	v_mov_b32_e32 v77, v75
	v_pk_add_f32 v[74:75], v[78:79], v[76:77]
	v_mul_f32_e32 v76, v28, v28
	v_mul_f32_e32 v77, v29, v29
	v_pk_add_f32 v[74:75], v[74:75], v[74:75] op_sel:[0,1] op_sel_hi:[1,0]
	v_mov_b32_e32 v73, v76
	v_mov_b32_e32 v75, v77
	v_pk_add_f32 v[72:73], v[72:73], v[74:75]
	v_mul_f32_e32 v74, v21, v21
	v_mul_f32_e32 v76, v23, v23
	v_mul_f32_e32 v78, v30, v30
	v_mul_f32_e32 v79, v31, v31
	v_pk_fma_f32 v[74:75], v[20:21], v[20:21], v[74:75] op_sel_hi:[1,1,0]
	v_pk_fma_f32 v[76:77], v[22:23], v[22:23], v[76:77] op_sel_hi:[1,1,0]
	v_mov_b32_e32 v75, v78
	v_mov_b32_e32 v77, v79
	v_pk_add_f32 v[74:75], v[74:75], v[76:77]
	s_lshl_b64 s[10:11], s[10:11], 11
	v_pk_add_f32 v[72:73], v[72:73], v[74:75]
	s_nop 0
	v_add_f32_e32 v72, v72, v73
	ds_bpermute_b32 v73, v51, v72
	s_waitcnt lgkmcnt(0)
	v_add_f32_e32 v72, v72, v73
	ds_bpermute_b32 v73, v80, v72
	s_waitcnt lgkmcnt(0)
	v_add_f32_e32 v72, v72, v73
	ds_bpermute_b32 v73, v81, v72
	s_waitcnt lgkmcnt(0)
	v_add_f32_e32 v72, v72, v73
	ds_bpermute_b32 v73, v82, v72
	s_waitcnt lgkmcnt(0)
	v_add_f32_e32 v72, v72, v73
	ds_bpermute_b32 v73, v83, v72
	s_waitcnt lgkmcnt(0)
	v_add_f32_e32 v72, v72, v73
	ds_bpermute_b32 v73, v84, v72
	s_waitcnt lgkmcnt(0)
	v_add_f32_e32 v72, v72, v73
	v_fmamk_f32 v72, v72, 0x3a800000, v209
	v_mul_f32_e32 v73, 0x4b800000, v72
	v_cmp_gt_f32_e32 vcc, s96, v72
	s_nop 1
	v_cndmask_b32_e32 v72, v72, v73, vcc
	v_rsq_f32_e32 v74, v72
	v_lshl_add_u64 v[72:73], v[52:53], 0, s[10:11]
	v_mul_f32_e32 v75, 0x45800000, v74
	v_cndmask_b32_e32 v74, v74, v75, vcc
	v_pk_mul_f32 v[76:77], v[74:75], v[4:5] op_sel_hi:[0,1]
	v_pk_mul_f32 v[78:79], v[74:75], v[6:7] op_sel_hi:[0,1]
	v_pk_fma_f32 v[78:79], v[68:69], v[78:79], v[34:35]
	v_pk_fma_f32 v[76:77], v[70:71], v[76:77], v[32:33]
	s_nop 0
	v_cvt_pk_bf16_f32 v76, v76, v77
	v_cvt_pk_bf16_f32 v77, v78, v79
	global_store_dwordx2 v[72:73], v[76:77], off sc1
	v_pk_mul_f32 v[76:77], v[74:75], v[12:13] op_sel_hi:[0,1]
	v_pk_mul_f32 v[78:79], v[74:75], v[14:15] op_sel_hi:[0,1]
	v_pk_fma_f32 v[78:79], v[56:57], v[78:79], v[38:39]
	v_pk_fma_f32 v[76:77], v[58:59], v[76:77], v[36:37]
	s_nop 0
	v_cvt_pk_bf16_f32 v76, v76, v77
	v_cvt_pk_bf16_f32 v77, v78, v79
	global_store_dwordx2 v[72:73], v[76:77], off offset:512 sc1
	v_pk_mul_f32 v[76:77], v[74:75], v[20:21] op_sel_hi:[0,1]
	v_pk_mul_f32 v[78:79], v[74:75], v[22:23] op_sel_hi:[0,1]
	v_pk_fma_f32 v[78:79], v[60:61], v[78:79], v[42:43]
	v_pk_fma_f32 v[76:77], v[62:63], v[76:77], v[40:41]
	s_nop 0
	v_cvt_pk_bf16_f32 v76, v76, v77
	v_cvt_pk_bf16_f32 v77, v78, v79
	global_store_dwordx2 v[72:73], v[76:77], off offset:1024 sc1
	v_pk_mul_f32 v[76:77], v[74:75], v[28:29] op_sel_hi:[0,1]
	v_pk_mul_f32 v[74:75], v[74:75], v[30:31] op_sel_hi:[0,1]
	v_pk_fma_f32 v[74:75], v[64:65], v[74:75], v[46:47]
	v_pk_fma_f32 v[76:77], v[66:67], v[76:77], v[44:45]
	s_nop 0
	v_cvt_pk_bf16_f32 v76, v76, v77
	v_cvt_pk_bf16_f32 v77, v74, v75
	global_store_dwordx2 v[72:73], v[76:77], off offset:1536 sc1
	s_andn2_b64 vcc, exec, s[12:13]
	s_cbranch_vccnz .LBB0_195
	s_branch .LBB0_203

; __device__ __forceinline__ void p_norm(const Args& a, int l, int lane, int wave, int bid, int G) {
;     ...
;             NORM_FINISH(v0, ra, gs, sh); if (hb) NORM_FINISH(v1, rb, gs, sh); if (hc) NORM_FINISH(v2, rc, gs, sh);
.LBB0_203:
	v_pk_mul_f32 v[72:73], v[2:3], v[2:3]
	v_pk_mul_f32 v[74:75], v[0:1], v[0:1]
	s_ashr_i32 s9, s8, 31
	v_pk_mov_b32 v[76:77], v[74:75], v[72:73] op_sel:[1,0]
	v_mov_b32_e32 v75, v73
	v_pk_add_f32 v[72:73], v[76:77], v[74:75]
	v_pk_mul_f32 v[74:75], v[10:11], v[10:11]
	v_pk_mul_f32 v[76:77], v[8:9], v[8:9]
	v_pk_add_f32 v[72:73], v[72:73], v[72:73] op_sel:[0,1] op_sel_hi:[1,0]
	v_pk_mov_b32 v[78:79], v[76:77], v[74:75] op_sel:[1,0]
	v_mov_b32_e32 v77, v75
	v_pk_add_f32 v[74:75], v[78:79], v[76:77]
	v_mul_f32_e32 v76, v24, v24
	v_mul_f32_e32 v77, v25, v25
	v_pk_add_f32 v[74:75], v[74:75], v[74:75] op_sel:[0,1] op_sel_hi:[1,0]
	v_mov_b32_e32 v73, v76
	v_mov_b32_e32 v75, v77
	v_pk_add_f32 v[72:73], v[72:73], v[74:75]
	v_mul_f32_e32 v74, v17, v17
	v_mul_f32_e32 v76, v19, v19
	v_mul_f32_e32 v78, v26, v26
	v_mul_f32_e32 v79, v27, v27
	v_pk_fma_f32 v[74:75], v[16:17], v[16:17], v[74:75] op_sel_hi:[1,1,0]
	v_pk_fma_f32 v[76:77], v[18:19], v[18:19], v[76:77] op_sel_hi:[1,1,0]
	v_mov_b32_e32 v75, v78
	v_mov_b32_e32 v77, v79
	v_pk_add_f32 v[74:75], v[74:75], v[76:77]
	s_lshl_b64 s[8:9], s[8:9], 11
	v_pk_add_f32 v[72:73], v[72:73], v[74:75]
	s_nop 0
	v_add_f32_e32 v72, v72, v73
	ds_bpermute_b32 v73, v51, v72
	s_waitcnt lgkmcnt(0)
	v_add_f32_e32 v72, v72, v73
	ds_bpermute_b32 v73, v80, v72
	s_waitcnt lgkmcnt(0)
	v_add_f32_e32 v72, v72, v73
	ds_bpermute_b32 v73, v81, v72
	s_waitcnt lgkmcnt(0)
	v_add_f32_e32 v72, v72, v73
	ds_bpermute_b32 v73, v82, v72
	s_waitcnt lgkmcnt(0)
	v_add_f32_e32 v72, v72, v73
	ds_bpermute_b32 v73, v83, v72
	s_waitcnt lgkmcnt(0)
	v_add_f32_e32 v72, v72, v73
	ds_bpermute_b32 v73, v84, v72
	s_waitcnt lgkmcnt(0)
	v_add_f32_e32 v72, v72, v73
	v_fmamk_f32 v72, v72, 0x3a800000, v209
	v_mul_f32_e32 v73, 0x4b800000, v72
	v_cmp_gt_f32_e32 vcc, s96, v72
	s_nop 1
	v_cndmask_b32_e32 v72, v72, v73, vcc
	v_rsq_f32_e32 v74, v72
	v_lshl_add_u64 v[72:73], v[52:53], 0, s[8:9]
	v_mul_f32_e32 v75, 0x45800000, v74
	v_cndmask_b32_e32 v74, v74, v75, vcc
	v_pk_mul_f32 v[76:77], v[74:75], v[0:1] op_sel_hi:[0,1]
	v_pk_mul_f32 v[78:79], v[74:75], v[2:3] op_sel_hi:[0,1]
	v_pk_fma_f32 v[78:79], v[68:69], v[78:79], v[34:35]
	v_pk_fma_f32 v[76:77], v[70:71], v[76:77], v[32:33]
	s_nop 0
	v_cvt_pk_bf16_f32 v76, v76, v77
	v_cvt_pk_bf16_f32 v77, v78, v79
	global_store_dwordx2 v[72:73], v[76:77], off sc1
	v_pk_mul_f32 v[76:77], v[74:75], v[8:9] op_sel_hi:[0,1]
	v_pk_mul_f32 v[78:79], v[74:75], v[10:11] op_sel_hi:[0,1]
	v_pk_fma_f32 v[78:79], v[56:57], v[78:79], v[38:39]
	v_pk_fma_f32 v[76:77], v[58:59], v[76:77], v[36:37]
	s_nop 0
	v_cvt_pk_bf16_f32 v76, v76, v77
	v_cvt_pk_bf16_f32 v77, v78, v79
	global_store_dwordx2 v[72:73], v[76:77], off offset:512 sc1
	v_pk_mul_f32 v[76:77], v[74:75], v[16:17] op_sel_hi:[0,1]
	v_pk_mul_f32 v[78:79], v[74:75], v[18:19] op_sel_hi:[0,1]
	v_pk_fma_f32 v[78:79], v[60:61], v[78:79], v[42:43]
	v_pk_fma_f32 v[76:77], v[62:63], v[76:77], v[40:41]
	s_nop 0
	v_cvt_pk_bf16_f32 v76, v76, v77
	v_cvt_pk_bf16_f32 v77, v78, v79
	global_store_dwordx2 v[72:73], v[76:77], off offset:1024 sc1
	v_pk_mul_f32 v[76:77], v[74:75], v[24:25] op_sel_hi:[0,1]
	v_pk_mul_f32 v[74:75], v[74:75], v[26:27] op_sel_hi:[0,1]
	v_pk_fma_f32 v[74:75], v[64:65], v[74:75], v[46:47]
	v_pk_fma_f32 v[76:77], v[66:67], v[76:77], v[44:45]
	s_nop 0
	v_cvt_pk_bf16_f32 v76, v76, v77
	v_cvt_pk_bf16_f32 v77, v74, v75
	global_store_dwordx2 v[72:73], v[76:77], off offset:1536 sc1
	s_branch .LBB0_195

; #define NORM_LOAD(V, ROW) do { const u32x2* xr_ = (const u32x2*)(X + (size_t)(ROW) * D); _Pragma("unroll") for (int j = 0; j < 4; ++j) { const u32x2 w_ = xr_[64 * j + lane]; \
;         V[j] = (f32x4){__uint_as_float(w_.x << 16), __uint_as_float(w_.x & 0xffff0000u), __uint_as_float(w_.y << 16), __uint_as_float(w_.y & 0xffff0000u)}; } } while (0)
; __device__ __forceinline__ void p_norm(const Args& a, int l, int lane, int wave, int bid, int G) {
;     ...
;     for (int row = MP + gw; row < M; row += NGW) {
;         const float* mp = mod + (size_t)(NPB + ((row - MP) >> 3)) * 3072;
;         f32x4 gs[4], sh[4], v0[4];
;         NORM_LOAD(v0, row);
; #pragma unroll
;         for (int j = 0; j < 4; ++j) { gs[j] = *((const f32x4*)g + 64 * j + lane) * (*((const f32x4*)(mp + D) + 64 * j + lane) + 1.0f); sh[j] = *((const f32x4*)mp + 64 * j + lane); }
;         NORM_FINISH(v0, row, gs, sh);
;     }
.LBB0_206:
	v_lshl_add_u64 v[8:9], v[0:1], 0, s[4:5]
	v_add_co_u32_e32 v10, vcc, 0xfe800000, v8
	s_ashr_i32 s1, s0, 3
	s_nop 0
	v_addc_co_u32_e32 v11, vcc, -1, v9, vcc
	global_load_dwordx2 v[58:59], v[10:11], off
	v_add_co_u32_e32 v8, vcc, 0xfe801000, v8
	s_add_i32 s1, s1, 4
	s_nop 0
	v_addc_co_u32_e32 v9, vcc, -1, v9, vcc
	global_load_dwordx2 v[60:61], v[8:9], off offset:-2560
	global_load_dwordx2 v[62:63], v[8:9], off offset:-3584
	global_load_dwordx2 v[64:65], v[8:9], off offset:-3072
	s_mul_hi_i32 s7, s1, 0x3000
	s_mulk_i32 s1, 0x3000
	s_add_u32 s6, s2, s1
	s_addc_u32 s7, s3, s7
	v_lshl_add_u64 v[20:21], s[6:7], 0, v[172:173]
	v_lshl_add_u64 v[16:17], v[20:21], 0, s[26:27]
	global_load_dwordx4 v[8:11], v[16:17], off offset:1024
	global_load_dwordx4 v[12:15], v[16:17], off offset:2048
	s_nop 0
	global_load_dwordx4 v[16:19], v[16:17], off offset:3072
	v_add_co_u32_e32 v20, vcc, s8, v20
	s_add_i32 s0, s0, s44
	s_nop 0
	v_addc_co_u32_e32 v21, vcc, 0, v21, vcc
	global_load_dwordx4 v[20:23], v[20:21], off
	s_nop 0
	global_load_dwordx4 v[24:27], v[48:49], off offset:1024
	global_load_dwordx4 v[28:31], v[48:49], off
	global_load_dwordx4 v[32:35], v[48:49], off offset:2048
	global_load_dwordx4 v[36:39], v[48:49], off offset:3072
	global_load_dwordx4 v[40:43], v172, s[6:7]
	global_load_dwordx4 v[44:47], v172, s[6:7] offset:1024
	global_load_dwordx4 v[50:53], v172, s[6:7] offset:2048
	global_load_dwordx4 v[54:57], v172, s[6:7] offset:3072
	s_add_i32 s1, s0, 0x4000
	s_cmpk_lt_i32 s1, 0x4400
	s_waitcnt vmcnt(15)
	v_lshlrev_b32_e32 v66, 16, v58
	v_and_b32_e32 v67, 0xffff0000, v58
	v_lshlrev_b32_e32 v58, 16, v59
	v_and_b32_e32 v59, 0xffff0000, v59
	s_waitcnt vmcnt(14)
	v_lshlrev_b32_e32 v69, 16, v60
	v_and_b32_e32 v71, 0xffff0000, v60
	v_mul_f32_e32 v68, v59, v59
	s_waitcnt vmcnt(13)
	v_lshlrev_b32_e32 v73, 16, v63
	v_lshlrev_b32_e32 v72, 16, v62
	v_and_b32_e32 v63, 0xffff0000, v63
	v_and_b32_e32 v62, 0xffff0000, v62
	v_mul_f32_e32 v70, v67, v67
	s_waitcnt vmcnt(12)
	v_lshlrev_b32_e32 v74, 16, v64
	v_and_b32_e32 v75, 0xffff0000, v64
	v_lshlrev_b32_e32 v64, 16, v65
	v_and_b32_e32 v65, 0xffff0000, v65
	v_pk_fma_f32 v[76:77], v[58:59], v[58:59], v[68:69] op_sel_hi:[1,1,0]
	v_pk_mul_f32 v[78:79], v[62:63], v[62:63]
	v_pk_fma_f32 v[80:81], v[66:67], v[66:67], v[70:71] op_sel_hi:[1,1,0]
	v_lshlrev_b32_e32 v60, 16, v61
	v_and_b32_e32 v61, 0xffff0000, v61
	v_mov_b32_e32 v83, v69
	v_mul_f32_e32 v70, v75, v75
	v_mul_f32_e32 v84, v65, v65
	v_pk_fma_f32 v[78:79], v[72:73], v[72:73], v[78:79]
	v_mov_b32_e32 v68, v80
	v_mov_b32_e32 v82, v76
	v_mul_f32_e32 v86, v71, v71
	v_mul_f32_e32 v87, v60, v60
	v_mul_f32_e32 v88, v61, v61
	v_pk_add_f32 v[76:77], v[80:81], v[76:77]
	v_pk_fma_f32 v[80:81], v[74:75], v[74:75], v[70:71] op_sel_hi:[1,1,0]
	v_pk_fma_f32 v[84:85], v[64:65], v[64:65], v[84:85] op_sel_hi:[1,1,0]
	v_pk_mul_f32 v[82:83], v[68:69], v[82:83]
	v_pk_add_f32 v[78:79], v[78:79], v[78:79] op_sel:[0,1] op_sel_hi:[1,0]
	v_mov_b32_e32 v81, v87
	v_mov_b32_e32 v85, v88
	v_mov_b32_e32 v77, v83
	v_mov_b32_e32 v79, v86
	v_pk_add_f32 v[80:81], v[80:81], v[84:85]
	v_pk_add_f32 v[76:77], v[76:77], v[78:79]
	s_waitcnt vmcnt(11)
	v_pk_add_f32 v[10:11], v[10:11], 1.0 op_sel_hi:[1,0]
	v_pk_add_f32 v[76:77], v[76:77], v[80:81]
	s_waitcnt vmcnt(7)
	v_pk_mul_f32 v[10:11], v[26:27], v[10:11]
	v_add_f32_e32 v68, v76, v77
	ds_bpermute_b32 v70, v2, v68
	v_mov_b32_e32 v76, v72
	v_pk_add_f32 v[8:9], v[8:9], 1.0 op_sel_hi:[1,0]
	v_mov_b32_e32 v77, v62
	v_pk_mul_f32 v[8:9], v[24:25], v[8:9]
	s_waitcnt lgkmcnt(0)
	v_add_f32_e32 v68, v68, v70
	ds_bpermute_b32 v70, v3, v68
	v_mov_b32_e32 v62, v73
	v_pk_add_f32 v[14:15], v[14:15], 1.0 op_sel_hi:[1,0]
	v_pk_add_f32 v[12:13], v[12:13], 1.0 op_sel_hi:[1,0]
	v_pk_add_f32 v[16:17], v[16:17], 1.0 op_sel_hi:[1,0]
	s_waitcnt lgkmcnt(0)
	v_add_f32_e32 v68, v68, v70
	ds_bpermute_b32 v72, v4, v68
	v_mov_b32_e32 v70, v69
	v_pk_add_f32 v[22:23], v[22:23], 1.0 op_sel_hi:[1,0]
	v_pk_add_f32 v[20:21], v[20:21], 1.0 op_sel_hi:[1,0]
	s_waitcnt vmcnt(5)
	v_pk_mul_f32 v[14:15], v[34:35], v[14:15]
	s_waitcnt lgkmcnt(0)
	v_add_f32_e32 v68, v68, v72
	ds_bpermute_b32 v69, v5, v68
	v_pk_mul_f32 v[12:13], v[32:33], v[12:13]
	s_waitcnt vmcnt(4)
	v_pk_mul_f32 v[16:17], v[36:37], v[16:17]
	v_pk_mul_f32 v[22:23], v[30:31], v[22:23]
	v_pk_mul_f32 v[20:21], v[28:29], v[20:21]
	s_waitcnt lgkmcnt(0)
	v_add_f32_e32 v68, v68, v69
	ds_bpermute_b32 v69, v6, v68
	v_pk_add_f32 v[18:19], v[18:19], 1.0 op_sel_hi:[1,0]
	s_waitcnt lgkmcnt(0)
	v_add_f32_e32 v26, v68, v69
	ds_bpermute_b32 v27, v7, v26
	v_pk_mul_f32 v[18:19], v[38:39], v[18:19]
	s_waitcnt lgkmcnt(0)
	v_add_f32_e32 v24, v26, v27
	v_fmamk_f32 v24, v24, 0x3a800000, v209
	v_mul_f32_e32 v25, 0x4b800000, v24
	v_cmp_gt_f32_e32 vcc, s96, v24
	s_nop 1
	v_cndmask_b32_e32 v24, v24, v25, vcc
	v_rsq_f32_e32 v24, v24
	s_nop 0
	v_mul_f32_e32 v25, 0x45800000, v24
	v_cndmask_b32_e32 v24, v24, v25, vcc
	v_pk_mul_f32 v[26:27], v[24:25], v[66:67] op_sel_hi:[0,1]
	v_pk_mul_f32 v[28:29], v[24:25], v[58:59] op_sel_hi:[0,1]
	v_pk_mul_f32 v[30:31], v[24:25], v[76:77] op_sel_hi:[0,1]
	v_pk_mul_f32 v[32:33], v[24:25], v[62:63] op_sel_hi:[0,1]
	v_pk_mul_f32 v[34:35], v[24:25], v[74:75] op_sel_hi:[0,1]
	v_pk_mul_f32 v[36:37], v[24:25], v[64:65] op_sel_hi:[0,1]
	s_waitcnt vmcnt(3)
	v_pk_fma_f32 v[22:23], v[22:23], v[28:29], v[42:43]
	v_pk_fma_f32 v[20:21], v[20:21], v[26:27], v[40:41]
	s_waitcnt vmcnt(2)
	v_pk_fma_f32 v[10:11], v[10:11], v[32:33], v[46:47]
	v_pk_fma_f32 v[8:9], v[8:9], v[30:31], v[44:45]
	s_waitcnt vmcnt(1)
	v_pk_fma_f32 v[14:15], v[14:15], v[36:37], v[52:53]
	v_pk_fma_f32 v[12:13], v[12:13], v[34:35], v[50:51]
	v_cvt_pk_bf16_f32 v20, v20, v21
	v_cvt_pk_bf16_f32 v21, v22, v23
	v_cvt_pk_bf16_f32 v8, v8, v9
	v_cvt_pk_bf16_f32 v9, v10, v11
	v_cvt_pk_bf16_f32 v10, v12, v13
	v_cvt_pk_bf16_f32 v11, v14, v15
	global_store_dwordx2 v[0:1], v[20:21], off sc1
	global_store_dwordx2 v[0:1], v[8:9], off offset:512 sc1
	global_store_dwordx2 v[0:1], v[10:11], off offset:1024 sc1
	v_pk_mul_f32 v[8:9], v[24:25], v[70:71] op_sel_hi:[0,1]
	v_pk_mul_f32 v[10:11], v[24:25], v[60:61] op_sel_hi:[0,1]
	s_waitcnt vmcnt(3)
	v_pk_fma_f32 v[10:11], v[18:19], v[10:11], v[56:57]
	v_pk_fma_f32 v[8:9], v[16:17], v[8:9], v[54:55]
	s_nop 0
	v_cvt_pk_bf16_f32 v8, v8, v9
	v_cvt_pk_bf16_f32 v9, v10, v11
	global_store_dwordx2 v[0:1], v[8:9], off offset:1536 sc1
	v_lshl_add_u64 v[0:1], v[0:1], 0, s[10:11]
	s_cbranch_scc1 .LBB0_206
